# MLA: next-tile K fragment prefetch during PV + three DMA pieces in the vector block, fourth at matrix block start
# baseline (speedup 1.0000x reference)
; #define KFRAG(da, dc, ks_) do { da = *(const LAS bf16x8*)(kb + r32 * KP + 16 * (ks_) + 8 * hf); dc = *(const LAS bf16x8*)(kb + (32 + r32) * KP + 16 * (ks_) + 8 * hf); } while (0)
; DI void mla_attn_phase(LAS unsigned char* lds, const bf16_t* Qg, const bf16_t* Kg, const bf16_t* Vtg, bf16_t* MIX) {
;     ...
;                     KFRAG(ka0, kc0_, 0); KFRAG(ka1, kc1_, 1);
.Lmla_nodma2:
	v_lshl_add_u64 v[216:217], v[216:217], 0, s[18:19]
	s_cmp_gt_i32 s40, s39
	s_cbranch_scc1 .LBB0_367
	s_waitcnt lgkmcnt(6)
	v_mfma_f32_32x32x16_bf16 v[64:79], v[144:147], v[80:83], v[64:79]
	v_mfma_f32_32x32x16_bf16 v[48:63], v[140:143], v[80:83], v[48:63]
	s_waitcnt lgkmcnt(0)
	v_mfma_f32_32x32x16_bf16 v[32:47], v[148:151], v[80:83], v[32:47]
	v_mfma_f32_32x32x16_bf16 v[16:31], v[152:155], v[80:83], v[16:31]
	ds_read_b128 v[80:83], v1 offset:13376
	ds_read_b128 v[96:99], v1 offset:17984
	ds_read_b128 v[100:103], v1 offset:22592
	ds_read_b128 v[104:107], v1 offset:27200
	v_mfma_f32_32x32x16_bf16 v[64:79], v[136:139], v[88:91], v[64:79]
	v_mfma_f32_32x32x16_bf16 v[48:63], v[12:15], v[88:91], v[48:63]
	v_mfma_f32_32x32x16_bf16 v[32:47], v[4:7], v[88:91], v[32:47]
	v_mfma_f32_32x32x16_bf16 v[16:31], v[8:11], v[88:91], v[16:31]
	ds_read_b128 v[4:7], v1 offset:13408
	ds_read_b128 v[8:11], v1 offset:18016
	ds_read_b128 v[12:15], v1 offset:22624
	ds_read_b128 v[88:91], v1 offset:27232
	s_add_i32 s30, s41, 1
	s_and_b32 s30, s30, 3
	s_lshl_b32 s30, s30, 15
	v_lshl_add_u32 v218, v166, 1, v230
	v_add_u32_e32 v218, s30, v218
	ds_read_b128 v[140:143], v218
	ds_read_b128 v[144:147], v218 offset:32
	ds_read_b128 v[148:151], v218 offset:6656
	ds_read_b128 v[152:155], v218 offset:6688
	s_waitcnt lgkmcnt(8)
	v_mfma_f32_32x32x16_bf16 v[64:79], v[80:83], v[84:87], v[64:79]
	v_mov_b32_e32 v233, v236
	v_mfma_f32_32x32x16_bf16 v[48:63], v[96:99], v[84:87], v[48:63]
	v_mfma_f32_32x32x16_bf16 v[32:47], v[100:103], v[84:87], v[32:47]
	v_mfma_f32_32x32x16_bf16 v[16:31], v[104:107], v[84:87], v[16:31]
	s_waitcnt lgkmcnt(4)
	v_mfma_f32_32x32x16_bf16 v[64:79], v[4:7], v[92:95], v[64:79]
	v_mfma_f32_32x32x16_bf16 v[48:63], v[8:11], v[92:95], v[48:63]
	v_mfma_f32_32x32x16_bf16 v[32:47], v[12:15], v[92:95], v[32:47]
	v_mfma_f32_32x32x16_bf16 v[16:31], v[88:91], v[92:95], v[16:31]
	s_branch .LBB0_371
